# grid barrier: L1 invalidate issued at arrival (overlaps the wait) instead of after release
# speedup vs baseline: 1.0393x; 1.0011x over previous
; __device__ __forceinline__ unsigned xb_ld(unsigned* p)              { return __hip_atomic_load(p, __ATOMIC_RELAXED, __HIP_MEMORY_SCOPE_AGENT); }
; __device__ __forceinline__ unsigned xb_add(unsigned* p, unsigned v) { return __hip_atomic_fetch_add(p, v, __ATOMIC_RELAXED, __HIP_MEMORY_SCOPE_AGENT); }
; #define XB_SPIN(cond, bar) do { unsigned _sp = 0; while (cond) { __builtin_amdgcn_s_sleep(3); \
;     if ((++_sp & 255u) == 0u) { if (xb_ld(&(bar)[XB_TMO])) break; if (_sp > XB_SPIN_CAP) { atomicAdd(&(bar)[XB_TMO], 1u); break; } } } } while (0)
; __device__ __forceinline__ void xcd_barrier(const XcdBarrier& b) {
;     ...
;     if (threadIdx.x == 0) {
;         unsigned* bar = b.bar;
;         __builtin_amdgcn_s_waitcnt(0);
;         unsigned nloc = b.st[0], nx = b.st[1];
;         if (nloc == 0u) { xcd_barrier_complete(bar, b.x, nloc, nx); b.st[0] = nloc; b.st[1] = nx; }
;         const unsigned old = xb_add(&bar[XB_XSUB(b.x)], 1u);
;         const unsigned gen = old / nloc;
;         if (old + 1u == (gen + 1u) * nloc) {
;             const unsigned og = xb_add(&bar[XB_TOP], 1u);
;             const unsigned tg = og / nx;
;             if (og + 1u == (tg + 1u) * nx) xb_add(&bar[XB_TOPGEN], 1u);
;             else XB_SPIN(xb_ld(&bar[XB_TOPGEN]) == tg, bar);
;             __builtin_amdgcn_fence(__ATOMIC_ACQUIRE, "agent");
;             xb_add(&bar[XB_XGEN(b.x)], 1u);
;             asm volatile("s_waitcnt vmcnt(0)" ::: "memory");
;         } else {
;             XB_SPIN(xb_ld(&bar[XB_XGEN(b.x)]) == gen, bar);
;             __builtin_amdgcn_fence(__ATOMIC_ACQUIRE, "agent");
;             asm volatile("s_waitcnt vmcnt(0)" ::: "memory");
.LBB0_513:
	v_readlane_b32 s2, v254, 43
	v_readlane_b32 s3, v254, 44
	v_cvt_f32_u32_e32 v0, v3
	v_sub_u32_e32 v5, 0, v3
	v_rcp_iflag_f32_e32 v0, v0
	s_nop 1
	global_atomic_add v4, v1, v242, s[2:3] sc0
	v_mul_f32_e32 v0, 0x4f7ffffe, v0
	v_cvt_u32_f32_e32 v0, v0
	v_mul_lo_u32 v5, v5, v0
	v_mul_hi_u32 v5, v0, v5
	v_add_u32_e32 v0, v0, v5
	s_waitcnt vmcnt(0)
	v_mul_hi_u32 v0, v4, v0
	v_mul_lo_u32 v5, v0, v3
	v_sub_u32_e32 v5, v4, v5
	v_add_u32_e32 v6, 1, v0
	v_cmp_ge_u32_e32 vcc, v5, v3
	v_add_u32_e32 v4, 1, v4
	s_nop 0
	v_cndmask_b32_e32 v0, v0, v6, vcc
	v_sub_u32_e32 v6, v5, v3
	v_cndmask_b32_e32 v5, v5, v6, vcc
	v_add_u32_e32 v6, 1, v0
	v_cmp_ge_u32_e32 vcc, v5, v3
	s_nop 1
	v_cndmask_b32_e32 v0, v0, v6, vcc
	v_mul_lo_u32 v5, v3, v0
	v_add_u32_e32 v3, v5, v3
	v_cmp_ne_u32_e32 vcc, v4, v3
	s_and_saveexec_b64 s[2:3], vcc
	s_xor_b64 s[10:11], exec, s[2:3]
	s_cbranch_execz .LBB0_527
	buffer_inv sc1
	v_readlane_b32 s2, v254, 45
	v_readlane_b32 s3, v254, 46
	s_waitcnt lgkmcnt(0)
	s_nop 3
	global_load_dword v2, v1, s[2:3] sc1
	s_waitcnt vmcnt(0)
	v_cmp_eq_u32_e32 vcc, v2, v0
	s_and_saveexec_b64 s[12:13], vcc
	s_cbranch_execz .LBB0_526
	s_mov_b32 s22, 1
	s_mov_b64 s[14:15], 0
	s_branch .LBB0_517

; __device__ __forceinline__ unsigned xb_ld(unsigned* p)              { return __hip_atomic_load(p, __ATOMIC_RELAXED, __HIP_MEMORY_SCOPE_AGENT); }
; __device__ __forceinline__ unsigned xb_add(unsigned* p, unsigned v) { return __hip_atomic_fetch_add(p, v, __ATOMIC_RELAXED, __HIP_MEMORY_SCOPE_AGENT); }
; #define XB_SPIN(cond, bar) do { unsigned _sp = 0; while (cond) { __builtin_amdgcn_s_sleep(3); \
;     if ((++_sp & 255u) == 0u) { if (xb_ld(&(bar)[XB_TMO])) break; if (_sp > XB_SPIN_CAP) { atomicAdd(&(bar)[XB_TMO], 1u); break; } } } } while (0)
; __device__ __forceinline__ void xcd_barrier(const XcdBarrier& b) {
;     ...
;         if (old + 1u == (gen + 1u) * nloc) {
;             const unsigned og = xb_add(&bar[XB_TOP], 1u);
;             const unsigned tg = og / nx;
;             if (og + 1u == (tg + 1u) * nx) xb_add(&bar[XB_TOPGEN], 1u);
;             else XB_SPIN(xb_ld(&bar[XB_TOPGEN]) == tg, bar);
;             __builtin_amdgcn_fence(__ATOMIC_ACQUIRE, "agent");
;             xb_add(&bar[XB_XGEN(b.x)], 1u);
;             asm volatile("s_waitcnt vmcnt(0)" ::: "memory");
;         } else {
;             XB_SPIN(xb_ld(&bar[XB_XGEN(b.x)]) == gen, bar);
;             __builtin_amdgcn_fence(__ATOMIC_ACQUIRE, "agent");
;             asm volatile("s_waitcnt vmcnt(0)" ::: "memory");
.LBB0_526:
	s_or_b64 exec, exec, s[12:13]
	s_waitcnt vmcnt(0)
	s_waitcnt vmcnt(0)
.LBB0_527:
	s_andn2_saveexec_b64 s[2:3], s[10:11]
	s_cbranch_execz .LBB0_545
	buffer_inv sc1
	s_mov_b64 s[10:11], exec
	v_mbcnt_lo_u32_b32 v0, s10, 0
	v_mbcnt_hi_u32_b32 v0, s11, v0
	v_cmp_eq_u32_e32 vcc, 0, v0
	s_and_saveexec_b64 s[2:3], vcc
	s_cbranch_execz .LBB0_530
	s_bcnt1_i32_b64 s10, s[10:11]
	v_mov_b32_e32 v3, s10
	v_readlane_b32 s10, v254, 47
	v_readlane_b32 s11, v254, 48
	s_nop 4
	global_atomic_add v3, v1, v3, s[10:11] sc0

; __device__ __forceinline__ unsigned xb_ld(unsigned* p)              { return __hip_atomic_load(p, __ATOMIC_RELAXED, __HIP_MEMORY_SCOPE_AGENT); }
; __device__ __forceinline__ unsigned xb_add(unsigned* p, unsigned v) { return __hip_atomic_fetch_add(p, v, __ATOMIC_RELAXED, __HIP_MEMORY_SCOPE_AGENT); }
; #define XB_SPIN(cond, bar) do { unsigned _sp = 0; while (cond) { __builtin_amdgcn_s_sleep(3); \
;     if ((++_sp & 255u) == 0u) { if (xb_ld(&(bar)[XB_TMO])) break; if (_sp > XB_SPIN_CAP) { atomicAdd(&(bar)[XB_TMO], 1u); break; } } } } while (0)
; __device__ __forceinline__ void xcd_barrier(const XcdBarrier& b) {
;     ...
;         if (old + 1u == (gen + 1u) * nloc) {
;             const unsigned og = xb_add(&bar[XB_TOP], 1u);
;             const unsigned tg = og / nx;
;             if (og + 1u == (tg + 1u) * nx) xb_add(&bar[XB_TOPGEN], 1u);
;             else XB_SPIN(xb_ld(&bar[XB_TOPGEN]) == tg, bar);
;             __builtin_amdgcn_fence(__ATOMIC_ACQUIRE, "agent");
;             xb_add(&bar[XB_XGEN(b.x)], 1u);
;             asm volatile("s_waitcnt vmcnt(0)" ::: "memory");
.LBB0_544:
	s_or_b64 exec, exec, s[10:11]
	v_readlane_b32 s2, v254, 45
	v_readlane_b32 s3, v254, 46
	s_waitcnt vmcnt(0)
	s_nop 2
	global_atomic_add v1, v242, s[2:3]
	s_waitcnt vmcnt(0)
